# combined: kv ssq loads hoisted (P3), q/kv row-sum shuffles by v_permlane swaps (P2), P9 seam fix-up with loads ahead of the tile decode and only the unit's own rows
# speedup vs baseline: 1.0051x; 1.0051x over previous
.LBB0_704:
	s_cmp_lt_i32 s87, 32
	s_cselect_b64 s[4:5], -1, 0
	s_cmp_gt_i32 s87, 31
	s_cselect_b64 s[2:3], -1, 0
	s_lshl_b32 s34, s87, 8
	s_add_i32 s34, s34, s46
	v_or_b32_e32 v172, s34, v200
	v_mul_u32_u24_e32 v248, 0x90, v172
	v_add_u32_e32 v249, 0x1200, v248
	global_load_dwordx4 v[216:219], v248, s[12:13] offset:48
	global_load_dwordx4 v[220:223], v248, s[12:13] offset:64
	global_load_dwordx4 v[224:227], v248, s[12:13] offset:2352
	global_load_dwordx4 v[228:231], v248, s[12:13] offset:2368
	global_load_dwordx4 v[232:235], v249, s[12:13] offset:48
	global_load_dwordx4 v[236:239], v249, s[12:13] offset:64
	global_load_dwordx4 v[240:243], v249, s[12:13] offset:2352
	global_load_dwordx4 v[244:247], v249, s[12:13] offset:2368
	v_mov_b32_e32 v150, 1.0
	s_and_b64 vcc, exec, s[2:3]
	v_mov_b32_e32 v152, 1.0
	s_cbranch_vccnz .LBB0_706
	v_mov_b64_e32 v[144:145], s[12:13]
	v_mad_i64_i32 v[148:149], s[6:7], v172, s53, v[144:145]
	s_waitcnt vmcnt(0)
	v_mov_b32_e32 v144, v216
	v_mov_b32_e32 v145, v217
	v_mov_b32_e32 v146, v218
	v_mov_b32_e32 v147, v219
	v_mov_b32_e32 v152, v220
	v_mov_b32_e32 v153, v221
	v_mov_b32_e32 v154, v222
	v_mov_b32_e32 v155, v223
	v_mov_b32_e32 v148, v144
	v_mov_b32_e32 v149, v152
	v_mov_b32_e32 v152, v145
	v_mov_b32_e32 v144, v146
	v_mov_b32_e32 v145, v154
	v_mov_b32_e32 v154, v147
	v_pk_add_f32 v[146:147], v[148:149], v[152:153]
	v_pk_add_f32 v[144:145], v[144:145], v[154:155]
	s_nop 0
	v_pk_add_f32 v[144:145], v[146:147], v[144:145]
	s_nop 0
	v_add_f32_e32 v144, v144, v145
	v_fmamk_f32 v144, v144, 0x3b800000, v170
	v_rsq_f32_e32 v152, v144
.LBB0_706:
	v_cndmask_b32_e64 v144, 0, 1, s[4:5]
	v_cmp_ne_u32_e64 s[10:11], 1, v144
	s_andn2_b64 vcc, exec, s[4:5]
	v_or_b32_e32 v149, 16, v172
	s_cbranch_vccnz .LBB0_708
	v_mov_b64_e32 v[144:145], s[12:13]
	v_mad_i64_i32 v[150:151], s[4:5], v149, s53, v[144:145]
	v_mov_b32_e32 v144, v224
	v_mov_b32_e32 v145, v225
	v_mov_b32_e32 v146, v226
	v_mov_b32_e32 v147, v227
	v_mov_b32_e32 v174, v228
	v_mov_b32_e32 v175, v229
	v_mov_b32_e32 v176, v230
	v_mov_b32_e32 v177, v231
	v_mov_b32_e32 v150, v144
	v_mov_b32_e32 v151, v174
	v_mov_b32_e32 v174, v145
	v_mov_b32_e32 v144, v146
	v_mov_b32_e32 v145, v176
	v_mov_b32_e32 v176, v147
	v_pk_add_f32 v[146:147], v[150:151], v[174:175]
	v_pk_add_f32 v[144:145], v[144:145], v[176:177]
	s_nop 0
	v_pk_add_f32 v[144:145], v[146:147], v[144:145]
	s_nop 0
	v_add_f32_e32 v144, v144, v145
	v_fmamk_f32 v144, v144, 0x3b800000, v170
	v_rsq_f32_e32 v150, v144
.LBB0_708:
	v_readlane_b32 s96, v253, 62
	v_mov_b32_e32 v144, 1.0
	s_and_b64 vcc, exec, s[10:11]
	v_or_b32_e32 v146, 32, v172
	v_mov_b32_e32 v147, 1.0
	v_readlane_b32 s97, v253, 63
	v_readlane_b32 s93, v253, 60
	v_readlane_b32 s92, v253, 61
	s_cbranch_vccnz .LBB0_710
	v_mov_b64_e32 v[154:155], s[12:13]
	v_mad_i64_i32 v[154:155], s[4:5], v146, s53, v[154:155]
	v_mov_b32_e32 v174, v232
	v_mov_b32_e32 v175, v233
	v_mov_b32_e32 v176, v234
	v_mov_b32_e32 v177, v235
	v_mov_b32_e32 v178, v236
	v_mov_b32_e32 v179, v237
	v_mov_b32_e32 v180, v238
	v_mov_b32_e32 v181, v239
	v_mov_b32_e32 v154, v174
	v_mov_b32_e32 v155, v178
	v_mov_b32_e32 v178, v175
	v_mov_b32_e32 v174, v176
	v_mov_b32_e32 v175, v180
	v_mov_b32_e32 v180, v177
	v_pk_add_f32 v[154:155], v[154:155], v[178:179]
	v_pk_add_f32 v[174:175], v[174:175], v[180:181]
	s_nop 0
	v_pk_add_f32 v[154:155], v[154:155], v[174:175]
	s_nop 0
	v_add_f32_e32 v145, v154, v155
	v_fmamk_f32 v145, v145, 0x3b800000, v170
	v_rsq_f32_e32 v147, v145
.LBB0_710:
	s_and_b64 vcc, exec, s[10:11]
	v_or_b32_e32 v145, 48, v172
	s_cbranch_vccnz .LBB0_712
	v_mov_b64_e32 v[154:155], s[12:13]
	v_mad_i64_i32 v[154:155], s[4:5], v145, s53, v[154:155]
	v_mov_b32_e32 v174, v240
	v_mov_b32_e32 v175, v241
	v_mov_b32_e32 v176, v242
	v_mov_b32_e32 v177, v243
	v_mov_b32_e32 v178, v244
	v_mov_b32_e32 v179, v245
	v_mov_b32_e32 v180, v246
	v_mov_b32_e32 v181, v247
	v_mov_b32_e32 v154, v174
	v_mov_b32_e32 v155, v178
	v_mov_b32_e32 v178, v175
	v_mov_b32_e32 v174, v176
	v_mov_b32_e32 v175, v180
	v_mov_b32_e32 v180, v177
	v_pk_add_f32 v[154:155], v[154:155], v[178:179]
	v_pk_add_f32 v[174:175], v[174:175], v[180:181]
	s_nop 0
	v_pk_add_f32 v[154:155], v[154:155], v[174:175]
	s_nop 0
	v_add_f32_e32 v144, v154, v155
	v_fmamk_f32 v144, v144, 0x3b800000, v170
	v_rsq_f32_e32 v144, v144
.LBB0_712:
	v_add_u32_e32 v250, 0x4800, v248
	v_add_u32_e32 v251, 0x5a00, v248
	global_load_dwordx4 v[216:219], v250, s[12:13] offset:48
	global_load_dwordx4 v[220:223], v250, s[12:13] offset:64
	global_load_dwordx4 v[224:227], v250, s[12:13] offset:2352
	global_load_dwordx4 v[228:231], v250, s[12:13] offset:2368
	global_load_dwordx4 v[232:235], v251, s[12:13] offset:48
	global_load_dwordx4 v[236:239], v251, s[12:13] offset:64
	global_load_dwordx4 v[240:243], v251, s[12:13] offset:2352
	global_load_dwordx4 v[244:247], v251, s[12:13] offset:2368
	s_cmp_lt_i32 s87, 16
	s_cselect_b64 s[4:5], -1, 0
	s_add_i32 s6, s34, 0xffffe000
	s_lshr_b32 s6, s6, 9
	s_mul_i32 s35, s6, 0x600
	s_addk_i32 s35, 0x1000
	s_mov_b64 s[6:7], -1
	s_and_b64 vcc, exec, s[2:3]
	s_cbranch_vccz .LBB0_714
	v_and_b32_e32 v148, 0x1cf, v172
	v_or_b32_e32 v154, s35, v148
	s_mov_b64 s[6:7], 0

.LBB0_760:
	s_and_b64 vcc, exec, s[10:11]
	v_mov_b32_e32 v66, s79
	s_cbranch_vccnz .LBB0_762
	v_add_u32_e32 v66, 0x80, v172
	v_mov_b64_e32 v[64:65], s[12:13]
	v_mad_i64_i32 v[68:69], s[2:3], v66, s53, v[64:65]
	s_nop 0
	s_waitcnt vmcnt(0)
	v_mov_b32_e32 v64, v216
	v_mov_b32_e32 v65, v217
	v_mov_b32_e32 v66, v218
	v_mov_b32_e32 v67, v219
	v_mov_b32_e32 v68, v220
	v_mov_b32_e32 v69, v221
	v_mov_b32_e32 v70, v222
	v_mov_b32_e32 v71, v223
	v_mov_b32_e32 v72, v64
	v_mov_b32_e32 v73, v68
	v_mov_b32_e32 v68, v65
	v_mov_b32_e32 v64, v66
	v_mov_b32_e32 v65, v70
	v_mov_b32_e32 v70, v67
	v_pk_add_f32 v[66:67], v[72:73], v[68:69]
	v_pk_add_f32 v[64:65], v[64:65], v[70:71]
	s_nop 0
	v_pk_add_f32 v[64:65], v[66:67], v[64:65]
	s_nop 0
	v_add_f32_e32 v64, v64, v65
	v_fmamk_f32 v64, v64, 0x3b800000, v170
	v_rsq_f32_e32 v66, v64
.LBB0_762:
	s_and_b64 vcc, exec, s[10:11]
	s_cbranch_vccnz .LBB0_766
	v_add_u32_e32 v67, 0x90, v172
	v_mov_b64_e32 v[64:65], s[12:13]
	v_mad_i64_i32 v[64:65], s[2:3], v67, s53, v[64:65]
	v_mov_b32_e32 v68, v224
	v_mov_b32_e32 v69, v225
	v_mov_b32_e32 v70, v226
	v_mov_b32_e32 v71, v227
	v_mov_b32_e32 v72, v228
	v_mov_b32_e32 v73, v229
	v_mov_b32_e32 v74, v230
	v_mov_b32_e32 v75, v231
	v_mov_b32_e32 v64, v68
	v_mov_b32_e32 v65, v72
	v_mov_b32_e32 v72, v69
	v_mov_b32_e32 v68, v70
	v_mov_b32_e32 v69, v74
	v_mov_b32_e32 v74, v71
	v_pk_add_f32 v[64:65], v[64:65], v[72:73]
	v_pk_add_f32 v[68:69], v[68:69], v[74:75]
	s_nop 0
	v_pk_add_f32 v[64:65], v[64:65], v[68:69]
	s_nop 0
	v_add_f32_e32 v64, v64, v65
	v_fmamk_f32 v64, v64, 0x3b800000, v170
	v_rsq_f32_e32 v67, v64
	s_and_b64 vcc, exec, s[10:11]
	s_cbranch_vccz .LBB0_767

.LBB0_767:
	v_add_u32_e32 v68, 0xa0, v172
	v_mov_b64_e32 v[64:65], s[12:13]
	v_mad_i64_i32 v[64:65], s[2:3], v68, s53, v[64:65]
	v_mov_b32_e32 v68, v232
	v_mov_b32_e32 v69, v233
	v_mov_b32_e32 v70, v234
	v_mov_b32_e32 v71, v235
	v_mov_b32_e32 v72, v236
	v_mov_b32_e32 v73, v237
	v_mov_b32_e32 v74, v238
	v_mov_b32_e32 v75, v239
	v_mov_b32_e32 v64, v68
	v_mov_b32_e32 v65, v72
	v_mov_b32_e32 v72, v69
	v_mov_b32_e32 v68, v70
	v_mov_b32_e32 v69, v74
	v_mov_b32_e32 v74, v71
	v_pk_add_f32 v[64:65], v[64:65], v[72:73]
	v_pk_add_f32 v[68:69], v[68:69], v[74:75]
	s_nop 0
	v_pk_add_f32 v[64:65], v[64:65], v[68:69]
	s_nop 0
	v_add_f32_e32 v64, v64, v65
	v_fmamk_f32 v64, v64, 0x3b800000, v170
	v_rsq_f32_e32 v64, v64
	s_and_b64 vcc, exec, s[10:11]
	s_cbranch_vccnz .LBB0_765
.LBB0_768:
	v_add_u32_e32 v65, 0xb0, v172
	v_mov_b64_e32 v[68:69], s[12:13]
	v_mad_i64_i32 v[72:73], s[2:3], v65, s53, v[68:69]
	s_nop 0
	v_mov_b32_e32 v68, v240
	v_mov_b32_e32 v69, v241
	v_mov_b32_e32 v70, v242
	v_mov_b32_e32 v71, v243
	v_mov_b32_e32 v72, v244
	v_mov_b32_e32 v73, v245
	v_mov_b32_e32 v74, v246
	v_mov_b32_e32 v75, v247
	v_mov_b32_e32 v76, v68
	v_mov_b32_e32 v77, v72
	v_mov_b32_e32 v72, v69
	v_mov_b32_e32 v68, v70
	v_mov_b32_e32 v69, v74
	v_mov_b32_e32 v74, v71
	v_pk_add_f32 v[70:71], v[76:77], v[72:73]
	v_pk_add_f32 v[68:69], v[68:69], v[74:75]
	s_nop 0
	v_pk_add_f32 v[68:69], v[70:71], v[68:69]
	s_nop 0
	v_add_f32_e32 v65, v68, v69
	v_fmamk_f32 v65, v65, 0x3b800000, v170
	v_rsq_f32_e32 v65, v65

.LBB0_1417:
	s_cmp_lt_i32 s94, 10
	s_cselect_b64 s[0:1], -1, 0
	s_cmp_gt_i32 s95, 9
	s_cselect_b64 s[2:3], -1, 0
	s_and_b64 s[0:1], s[0:1], s[2:3]
	s_andn2_b64 vcc, exec, s[0:1]
	s_cbranch_vccnz .LBB0_1500
	s_cmpk_lt_i32 s93, 0x100
	v_readfirstlane_b32 s0, v215
	s_cbranch_scc0 .LBB0_1446
	s_mov_b64 s[6:7], exec
	v_cmp_gt_u32_e32 vcc, 0x160, v215
	s_and_b64 exec, exec, vcc
	s_cbranch_execz .Lfx_a_done
	s_lshr_b32 s36, s93, 7
	s_and_b32 s35, s93, 7
	s_lshl_b32 s35, s35, 2
	s_bfe_u32 s12, s93, 0x20003
	s_or_b32 s35, s35, s12
	s_mul_i32 s8, s36, 0x580
	v_lshl_add_u32 v0, v215, 2, s8
	v_lshlrev_b32_e32 v1, 2, v0
	v_add_u32_e32 v2, 0x2c00, v1
	v_add_u32_e32 v3, 0x5800, v1
	v_add_u32_e32 v4, 0x8400, v1
	v_add_u32_e32 v5, 0xb000, v1
	v_add_u32_e32 v6, 0xdc00, v1
	v_add_u32_e32 v7, 0x10800, v1
	v_add_u32_e32 v8, 0x13400, v1
	v_lshlrev_b32_e32 v9, 1, v0
	v_add_u32_e32 v10, 0x1600, v9
	v_readlane_b32 s8, v253, 33
	v_readlane_b32 s9, v253, 34
	v_readlane_b32 s10, v253, 35
	v_readlane_b32 s11, v253, 36
	s_add_u32 s26, s74, 0x8000000
	s_addc_u32 s27, s75, 0
	s_add_u32 s28, s74, 0xc000000
	s_addc_u32 s29, s75, 0
	s_nop 2
	global_load_dwordx4 v[16:19], v1, s[8:9]
	global_load_dwordx4 v[20:23], v2, s[8:9]
	s_add_u32 s12, s8, 0x5800
	s_addc_u32 s13, s9, 0
	global_load_dwordx4 v[24:27], v1, s[12:13]
	global_load_dwordx4 v[28:31], v2, s[12:13]
	s_add_u32 s12, s8, 0xb000
	s_addc_u32 s13, s9, 0
	global_load_dwordx4 v[32:35], v1, s[12:13]
	global_load_dwordx4 v[36:39], v2, s[12:13]
	global_load_dwordx4 v[40:43], v1, s[10:11]
	global_load_dwordx4 v[44:47], v2, s[10:11]
	s_lshl_b32 s18, s35, 8
	s_movk_i32 s12, 0x3ff
	s_cmp_lt_u32 s18, 0x1000
	s_cselect_b32 s19, 0xff, s12
	s_and_b32 s19, s18, s19
	s_cmp_lg_u32 s19, 0
	s_cselect_b32 s19, 1, 0
	s_cmp_lt_u32 s18, 0x2000
	s_cselect_b32 s30, s19, 0
	s_cmp_eq_u32 s30, 0
	s_cbranch_scc1 .Lfx_l0
	s_lshr_b32 s19, s18, 6
	s_mul_i32 s19, s19, 0x16000
	s_add_u32 s20, s26, s19
	s_addc_u32 s21, s27, 0
	s_sub_u32 s20, s20, 0xb000
	s_subb_u32 s21, s21, 0
	global_load_dwordx4 v[48:51], v1, s[20:21]
	global_load_dwordx4 v[52:55], v2, s[20:21]
	global_load_dwordx4 v[56:59], v3, s[20:21]
	global_load_dwordx4 v[60:63], v4, s[20:21]
	global_load_dwordx4 v[64:67], v5, s[20:21]
	global_load_dwordx4 v[68:71], v6, s[20:21]
	global_load_dwordx4 v[72:75], v7, s[20:21]
	global_load_dwordx4 v[76:79], v8, s[20:21]
.Lfx_l0:
	s_lshl_b32 s18, s35, 8
	s_add_i32 s18, s18, 64
	s_movk_i32 s12, 0x3ff
	s_cmp_lt_u32 s18, 0x1000
	s_cselect_b32 s19, 0xff, s12
	s_and_b32 s19, s18, s19
	s_cmp_lg_u32 s19, 0
	s_cselect_b32 s19, 1, 0
	s_cmp_lt_u32 s18, 0x2000
	s_cselect_b32 s31, s19, 0
	s_cmp_eq_u32 s31, 0
	s_cbranch_scc1 .Lfx_l1
	s_lshr_b32 s19, s18, 6
	s_mul_i32 s19, s19, 0x16000
	s_add_u32 s20, s26, s19
	s_addc_u32 s21, s27, 0
	s_sub_u32 s20, s20, 0xb000
	s_subb_u32 s21, s21, 0
	global_load_dwordx4 v[80:83], v1, s[20:21]
	global_load_dwordx4 v[84:87], v2, s[20:21]
	global_load_dwordx4 v[88:91], v3, s[20:21]
	global_load_dwordx4 v[92:95], v4, s[20:21]
	global_load_dwordx4 v[96:99], v5, s[20:21]
	global_load_dwordx4 v[100:103], v6, s[20:21]
	global_load_dwordx4 v[104:107], v7, s[20:21]
	global_load_dwordx4 v[108:111], v8, s[20:21]
.Lfx_l1:
	s_lshl_b32 s18, s35, 8
	s_add_i32 s18, s18, 128
	s_movk_i32 s12, 0x3ff
	s_cmp_lt_u32 s18, 0x1000
	s_cselect_b32 s19, 0xff, s12
	s_and_b32 s19, s18, s19
	s_cmp_lg_u32 s19, 0
	s_cselect_b32 s19, 1, 0
	s_cmp_lt_u32 s18, 0x2000
	s_cselect_b32 s32, s19, 0
	s_cmp_eq_u32 s32, 0
	s_cbranch_scc1 .Lfx_l2
	s_lshr_b32 s19, s18, 6
	s_mul_i32 s19, s19, 0x16000
	s_add_u32 s20, s26, s19
	s_addc_u32 s21, s27, 0
	s_sub_u32 s20, s20, 0xb000
	s_subb_u32 s21, s21, 0
	global_load_dwordx4 v[112:115], v1, s[20:21]
	global_load_dwordx4 v[116:119], v2, s[20:21]
	global_load_dwordx4 v[120:123], v3, s[20:21]
	global_load_dwordx4 v[124:127], v4, s[20:21]
	global_load_dwordx4 v[128:131], v5, s[20:21]
	global_load_dwordx4 v[132:135], v6, s[20:21]
	global_load_dwordx4 v[136:139], v7, s[20:21]
	global_load_dwordx4 v[140:143], v8, s[20:21]
.Lfx_l2:
	s_lshl_b32 s18, s35, 8
	s_add_i32 s18, s18, 192
	s_movk_i32 s12, 0x3ff
	s_cmp_lt_u32 s18, 0x1000
	s_cselect_b32 s19, 0xff, s12
	s_and_b32 s19, s18, s19
	s_cmp_lg_u32 s19, 0
	s_cselect_b32 s19, 1, 0
	s_cmp_lt_u32 s18, 0x2000
	s_cselect_b32 s33, s19, 0
	s_cmp_eq_u32 s33, 0
	s_cbranch_scc1 .Lfx_l3
	s_lshr_b32 s19, s18, 6
	s_mul_i32 s19, s19, 0x16000
	s_add_u32 s20, s26, s19
	s_addc_u32 s21, s27, 0
	s_sub_u32 s20, s20, 0xb000
	s_subb_u32 s21, s21, 0
	global_load_dwordx4 v[144:147], v1, s[20:21]
	global_load_dwordx4 v[148:151], v2, s[20:21]
	global_load_dwordx4 v[152:155], v3, s[20:21]
	global_load_dwordx4 v[156:159], v4, s[20:21]
	global_load_dwordx4 v[160:163], v5, s[20:21]
	global_load_dwordx4 v[164:167], v6, s[20:21]
	global_load_dwordx4 v[168:171], v7, s[20:21]
	global_load_dwordx4 v[172:175], v8, s[20:21]
.Lfx_l3:
	s_lshl_b32 s18, s35, 8
	s_add_i32 s18, s18, 256
	s_movk_i32 s12, 0x3ff
	s_cmp_lt_u32 s18, 0x1000
	s_cselect_b32 s19, 0xff, s12
	s_and_b32 s19, s18, s19
	s_cmp_lg_u32 s19, 0
	s_cselect_b32 s19, 1, 0
	s_cmp_lt_u32 s18, 0x2000
	s_cselect_b32 s34, s19, 0
	s_cmp_eq_u32 s34, 0
	s_cbranch_scc1 .Lfx_l4
	s_lshr_b32 s19, s18, 6
	s_mul_i32 s19, s19, 0x16000
	s_add_u32 s20, s26, s19
	s_addc_u32 s21, s27, 0
	s_sub_u32 s20, s20, 0xb000
	s_subb_u32 s21, s21, 0
	global_load_dwordx4 v[176:179], v1, s[20:21]
	global_load_dwordx4 v[180:183], v2, s[20:21]
	global_load_dwordx4 v[184:187], v3, s[20:21]
	global_load_dwordx4 v[188:191], v4, s[20:21]
	global_load_dwordx4 v[192:195], v5, s[20:21]
	global_load_dwordx4 v[196:199], v6, s[20:21]
	global_load_dwordx4 v[200:203], v7, s[20:21]
	global_load_dwordx4 v[204:207], v8, s[20:21]

.Lfx_a_done:
	s_mov_b64 exec, s[6:7]
	s_ashr_i32 s1, s93, 31
	s_lshr_b32 s1, s1, 25
	s_add_i32 s2, s93, s1
	s_ashr_i32 s1, s2, 7
	s_and_b32 s2, s2, 0xffffff80
	s_sub_i32 s2, s93, s2
	s_cmpk_gt_i32 s2, 0x7f
	s_cbranch_scc1 .LBB0_1421
	s_ashr_i32 s3, s2, 31
	s_lshr_b32 s3, s3, 29
	s_add_i32 s3, s2, s3
	s_ashr_i32 s4, s3, 3
	s_and_b32 s3, s3, -8
	s_sub_i32 s2, s2, s3
	s_lshl_b32 s3, s2, 4
	s_cmp_lt_i32 s2, 0
	s_mul_i32 s2, s2, 17
	s_cselect_b32 s2, s2, s3
	s_add_i32 s2, s2, s4
	s_ashr_i32 s3, s2, 31
	s_lshr_b32 s3, s3, 28
	s_add_i32 s3, s2, s3
	s_ashr_i32 s4, s3, 4
	s_lshl_b32 s4, s4, 2
	s_sub_i32 s5, 32, s4
	s_min_i32 s5, s5, 4
	s_abs_i32 s6, s5
	v_cvt_f32_u32_e32 v0, s6
	s_sub_i32 s8, 0, s6
	s_and_b32 s3, s3, -16
	s_sub_i32 s2, s2, s3
	v_rcp_iflag_f32_e32 v0, v0
	s_abs_i32 s3, s2
	s_xor_b32 s7, s2, s5
	s_ashr_i32 s7, s7, 31
	v_mul_f32_e32 v0, 0x4f7ffffe, v0
	v_cvt_u32_f32_e32 v0, v0
	s_nop 0
	v_readfirstlane_b32 s9, v0
	s_mul_i32 s8, s8, s9
	s_mul_hi_u32 s8, s9, s8
	s_add_i32 s9, s9, s8
	s_mul_hi_u32 s8, s3, s9
	s_mul_i32 s9, s8, s6
	s_sub_i32 s3, s3, s9
	s_add_i32 s10, s8, 1
	s_sub_i32 s9, s3, s6
	s_cmp_ge_u32 s3, s6
	s_cselect_b32 s8, s10, s8
	s_cselect_b32 s3, s9, s3
	s_add_i32 s9, s8, 1
	s_cmp_ge_u32 s3, s6
	s_cselect_b32 s3, s9, s8
	s_xor_b32 s3, s3, s7
	s_sub_i32 s44, s3, s7
	s_mul_i32 s3, s44, s5
	s_sub_i32 s2, s2, s3
	s_add_i32 s45, s4, s2
.LBB0_1421:
	s_mov_b64 s[6:7], exec
	v_cmp_gt_u32_e32 vcc, 0x160, v215
	s_and_b64 exec, exec, vcc
	s_cbranch_execz .Lfx_done
	s_mul_i32 s8, s1, 0x580
	v_lshl_add_u32 v0, v215, 2, s8
	v_lshlrev_b32_e32 v9, 1, v0
	v_add_u32_e32 v10, 0x1600, v9
	s_add_u32 s28, s74, 0xc000000
	s_addc_u32 s29, s75, 0
	s_waitcnt vmcnt(0)
	s_cmp_eq_u32 s30, 0
	s_cbranch_scc1 .Lfx_c0
	s_lshl_b32 s18, s45, 8
	s_add_i32 s18, s18, -1
	s_mul_i32 s19, s18, 0x1600
	s_add_u32 s22, s28, s19
	s_addc_u32 s23, s29, 0
	v_pk_fma_f32 v[208:209], v[56:57], v[16:17], v[40:41]
	v_pk_fma_f32 v[210:211], v[58:59], v[18:19], v[42:43]
	v_pk_fma_f32 v[208:209], v[64:65], v[24:25], v[208:209]
	v_pk_fma_f32 v[210:211], v[66:67], v[26:27], v[210:211]
	v_pk_fma_f32 v[208:209], v[72:73], v[32:33], v[208:209]
	v_pk_fma_f32 v[210:211], v[74:75], v[34:35], v[210:211]
	v_pk_fma_f32 v[12:13], v[60:61], v[20:21], v[44:45]
	v_pk_fma_f32 v[14:15], v[62:63], v[22:23], v[46:47]
	v_pk_fma_f32 v[12:13], v[68:69], v[28:29], v[12:13]
	v_pk_fma_f32 v[14:15], v[70:71], v[30:31], v[14:15]
	v_pk_fma_f32 v[12:13], v[76:77], v[36:37], v[12:13]
	v_pk_fma_f32 v[14:15], v[78:79], v[38:39], v[14:15]
	v_pk_mul_f32 v[216:217], v[208:209], v[222:223]
	v_pk_mul_f32 v[218:219], v[210:211], v[222:223]
	v_exp_f32_e32 v216, v216
	v_exp_f32_e32 v217, v217
	v_exp_f32_e32 v218, v218
	v_exp_f32_e32 v219, v219
	v_pk_add_f32 v[216:217], v[216:217], 1.0 op_sel_hi:[1,0]
	v_pk_add_f32 v[218:219], v[218:219], 1.0 op_sel_hi:[1,0]
	v_rcp_f32_e32 v216, v216
	v_rcp_f32_e32 v217, v217
	v_rcp_f32_e32 v218, v218
	v_rcp_f32_e32 v219, v219
	v_pk_mul_f32 v[208:209], v[208:209], v[216:217]
	v_pk_mul_f32 v[210:211], v[210:211], v[218:219]
	v_pk_mul_f32 v[208:209], v[208:209], v[12:13]
	v_pk_mul_f32 v[210:211], v[210:211], v[14:15]
	v_cvt_pk_bf16_f32 v226, v208, v209
	v_cvt_pk_bf16_f32 v227, v210, v211
	global_store_dwordx2 v10, v[226:227], s[22:23]

.Lfx_c3:
	s_cmp_eq_u32 s34, 0
	s_cbranch_scc1 .Lfx_c4
	s_lshl_b32 s18, s45, 8
	s_add_i32 s18, s18, 255
	s_mul_i32 s19, s18, 0x1600
	s_add_u32 s22, s28, s19
	s_addc_u32 s23, s29, 0
	v_pk_fma_f32 v[208:209], v[176:177], v[16:17], v[40:41]
	v_pk_fma_f32 v[210:211], v[178:179], v[18:19], v[42:43]
	v_pk_fma_f32 v[208:209], v[184:185], v[24:25], v[208:209]
	v_pk_fma_f32 v[210:211], v[186:187], v[26:27], v[210:211]
	v_pk_fma_f32 v[208:209], v[192:193], v[32:33], v[208:209]
	v_pk_fma_f32 v[210:211], v[194:195], v[34:35], v[210:211]
	v_pk_fma_f32 v[12:13], v[180:181], v[20:21], v[44:45]
	v_pk_fma_f32 v[14:15], v[182:183], v[22:23], v[46:47]
	v_pk_fma_f32 v[12:13], v[188:189], v[28:29], v[12:13]
	v_pk_fma_f32 v[14:15], v[190:191], v[30:31], v[14:15]
	v_pk_fma_f32 v[12:13], v[196:197], v[36:37], v[12:13]
	v_pk_fma_f32 v[14:15], v[198:199], v[38:39], v[14:15]
	v_pk_mul_f32 v[216:217], v[208:209], v[222:223]
	v_pk_mul_f32 v[218:219], v[210:211], v[222:223]
	v_exp_f32_e32 v216, v216
	v_exp_f32_e32 v217, v217
	v_exp_f32_e32 v218, v218
	v_exp_f32_e32 v219, v219
	v_pk_add_f32 v[216:217], v[216:217], 1.0 op_sel_hi:[1,0]
	v_pk_add_f32 v[218:219], v[218:219], 1.0 op_sel_hi:[1,0]
	v_rcp_f32_e32 v216, v216
	v_rcp_f32_e32 v217, v217
	v_rcp_f32_e32 v218, v218
	v_rcp_f32_e32 v219, v219
	v_pk_mul_f32 v[208:209], v[208:209], v[216:217]
	v_pk_mul_f32 v[210:211], v[210:211], v[218:219]
	v_pk_mul_f32 v[208:209], v[208:209], v[12:13]
	v_pk_mul_f32 v[210:211], v[210:211], v[14:15]
	v_cvt_pk_bf16_f32 v224, v208, v209
	v_cvt_pk_bf16_f32 v225, v210, v211
	global_store_dwordx2 v9, v[224:225], s[22:23]
.Lfx_c4:
.Lfx_done:
	s_mov_b64 exec, s[6:7]
	s_waitcnt vmcnt(0)
	s_barrier
	v_lshlrev_b32_e32 v2, 4, v215
	v_and_b32_e32 v0, 32, v215
	v_bitop3_b32 v1, v2, v0, 48 bitop3:0x6c
	s_waitcnt vmcnt(0)
	v_and_b32_e32 v10, 64, v215
	v_or_b32_e32 v0, v1, v10
	v_lshrrev_b32_e32 v4, 1, v0
	v_lshrrev_b32_e32 v0, 1, v215
	v_lshrrev_b32_e32 v5, 5, v215
	v_and_b32_e32 v0, 24, v0
	v_and_b32_e32 v5, 4, v5
	v_bfe_u32 v6, v215, 2, 2
	s_add_u32 s26, s74, 0xc000000
	v_bfe_u32 v3, v215, 2, 4
	v_or3_b32 v5, v5, v6, v0
	v_lshrrev_b32_e32 v6, 3, v215
	s_movk_i32 s2, 0x70
	s_addc_u32 s27, s75, 0
	v_and_or_b32 v7, v6, s2, v3
	s_movk_i32 s2, 0x60
	v_add_u32_e32 v2, 0x2000, v2
	s_add_u32 s28, s74, 0x1300000
	v_and_or_b32 v6, v6, s2, v5
	v_lshrrev_b32_e32 v2, 7, v2
	s_movk_i32 s2, 0xf0
	s_mul_i32 s18, s1, 0x580
	s_addc_u32 s29, s75, 0
	v_and_or_b32 v3, v2, s2, v3
	s_movk_i32 s2, 0xe0
	s_ashr_i32 s19, s18, 31
	v_and_or_b32 v2, v2, s2, v5
	s_lshl_b64 s[2:3], s[18:19], 1
	s_add_u32 s5, s28, s2
	s_addc_u32 s6, s29, s3
	s_add_u32 s7, s26, s2
	s_addc_u32 s8, s27, s3
	s_lshr_b32 s4, s0, 6
	s_lshr_b32 s1, s0, 8
	s_lshl_b32 s30, s4, 10
	s_mul_i32 s3, s44, 0x160000
	v_mul_u32_u24_e32 v6, 0xb00, v6
	s_mul_hi_i32 s2, s44, 0x160000
	s_add_u32 s20, s5, s3
	v_or_b32_e32 v6, v6, v4
	s_addc_u32 s21, s6, s2
	s_add_i32 s31, s30, 0
	v_lshlrev_b32_e32 v130, 1, v6
	v_mul_u32_u24_e32 v2, 0xb00, v2
	s_add_i32 m0, s31, 0x10000
	v_or_b32_e32 v2, v2, v4
	global_load_lds_dwordx4 v130, s[20:21]
	s_add_i32 m0, s31, 0x12000
	v_lshlrev_b32_e32 v134, 1, v2
	s_add_u32 s2, s20, 0xb0000
	global_load_lds_dwordx4 v134, s[20:21]
	s_addc_u32 s3, s21, 0
	s_add_i32 m0, s31, 0x14000
	s_mul_i32 s10, s45, 0x160000
	global_load_lds_dwordx4 v130, s[2:3]
	s_add_i32 m0, s31, 0x16000
	v_mul_u32_u24_e32 v11, 0xb00, v7
	s_mul_hi_i32 s9, s45, 0x160000
	global_load_lds_dwordx4 v134, s[2:3]
	s_add_u32 s2, s7, s10
	v_or_b32_e32 v7, v4, v11
	v_mul_u32_u24_e32 v12, 0xb00, v3
	s_addc_u32 s3, s8, s9
	s_add_i32 s33, s31, 0x2000
	v_lshlrev_b32_e32 v128, 1, v7
	v_or_b32_e32 v3, v12, v4
	s_mov_b32 m0, s31
	s_add_u32 s6, s2, 0xb0000
	v_lshlrev_b32_e32 v132, 1, v3
	global_load_lds_dwordx4 v128, s[2:3]
	s_mov_b32 m0, s33
	s_addc_u32 s7, s3, 0
	s_add_i32 s34, s31, 0x4000
	global_load_lds_dwordx4 v132, s[2:3]
	s_mov_b32 m0, s34
	s_add_i32 s35, s31, 0x6000
	global_load_lds_dwordx4 v128, s[6:7]
	s_mov_b32 m0, s35
	v_mov_b32_e32 v137, 0
	global_load_lds_dwordx4 v132, s[6:7]
	v_mov_b32_e32 v131, v137
	v_mov_b32_e32 v135, v137
	v_mov_b32_e32 v129, v137
	v_mov_b32_e32 v133, v137
	s_cmp_eq_u32 s1, 1
	s_mov_b32 s5, 0
	v_lshl_add_u64 v[8:9], s[20:21], 0, v[130:131]
	v_lshl_add_u64 v[6:7], s[20:21], 0, v[134:135]
	v_lshl_add_u64 v[2:3], s[2:3], 0, v[128:129]
	s_cselect_b64 s[6:7], -1, 0
	s_cmp_lg_u32 s1, 1
	v_lshl_add_u64 v[4:5], s[2:3], 0, v[132:133]
	s_cbranch_scc1 .LBB0_1423
	s_barrier
